# plus: tail 40% of W3A conversion done by the 64 workgroups idle during adaLN chunk 0 (guarded by grid==256)
# baseline (speedup 1.0000x reference)
; #define LAS __attribute__((address_space(3)))
; __global__ void __launch_bounds__(NWAVES * 64, 2) mk_fwd(Args args) {
;     extern __shared__ __attribute__((aligned(16))) unsigned char lds[];
;     Frame F;
;     F.lds = (LAS unsigned char*)lds;
;     F.MISC = (volatile LAS unsigned*)(F.lds + MISC_OFF);
;     F.tid = threadIdx.x; F.lane = F.tid & 63; F.wave = __builtin_amdgcn_readfirstlane(F.tid >> 6);
;     F.G = gridDim.x; { const int bx = blockIdx.x; F.vcu = (F.G % 8 == 0) ? (bx % 8) * (F.G / 8) + bx / 8 : bx; }
_Z6mk_fwd4Args:
	s_mov_b32 s98, 0
	s_movk_i32 s99, 0x2b00
	s_load_dword s33, s[0:1], 0xd8
	s_load_dwordx2 s[94:95], s[0:1], 0xd0
	s_mov_b32 s50, s2
	s_add_u32 s2, s0, 0xd8
	s_addc_u32 s3, s1, 0
	v_readfirstlane_b32 s24, v0
	v_writelane_b32 v252, s2, 0
	s_nop 1
	v_writelane_b32 v252, s3, 1
	s_waitcnt lgkmcnt(0)
	s_and_b32 s3, s33, 7
	s_mov_b32 s2, 0
	s_cmp_lg_u32 s3, 0
	v_writelane_b32 v252, s50, 2
	s_cbranch_scc1 .LBB0_2
	s_ashr_i32 s4, s50, 31
	s_lshr_b32 s4, s4, 29
	s_add_i32 s4, s50, s4
	s_and_b32 s5, s4, -8
	s_ashr_i32 s3, s33, 3
	s_sub_i32 s5, s50, s5
	s_mul_i32 s3, s3, s5
	s_ashr_i32 s4, s4, 3
	s_add_i32 s3, s3, s4
	v_writelane_b32 v252, s3, 2

; #define SEAM(k) do { if (IN(k) && IN((k) + 1)) xcd_barrier(bar); } while (0)
; template <int JOB>
; __device__ __forceinline__ void conv_job(Frame& F, const Args& A, int rank, int nw) {
;     ...
;     for (int it = rank; it < N; it += nw) {
;         if constexpr (JOB == JOB_W1A) p0_transpose_item8<1>(A.in[I_W1A], D, FF, ws + WS_W13A, S_W13, scr, it, F.lane);
;         if constexpr (JOB == JOB_W3A) p0_transpose_item8<2>(A.in[I_W3A], D, FF, ws + WS_W13A, S_W13, scr, it, F.lane);
; __global__ void __launch_bounds__(NWAVES * 64, 2) mk_fwd(Args args) {
;     ...
;         for (int rep = 0; rep < REPS(0); ++rep) { if (rep) xcd_barrier(bar);  csilu_phase(F, args); { const int rank = F.vcu * NWAVES + F.wave, nw = F.G * NWAVES; conv_job<JOB_W1A>(F, args, rank, nw); conv_job<JOB_W3A>(F, args, rank, nw); }  } } SEAM(0);
.Lconv_entry:
	s_cmp_lg_u32 s98, 0
	s_cbranch_scc1 .Lconv_e2
	s_cmpk_eq_i32 s33, 0x100
	s_cbranch_scc0 .Lconv_e2
	s_movk_i32 s99, 0x19c8

; #define SEAM(k) do { if (IN(k) && IN((k) + 1)) xcd_barrier(bar); } while (0)
; __device__ __forceinline__ void mod_chunk_partials(Frame& F, const Args& A, int chunk, int rank, int nwg) {
; #pragma unroll 1
;     for (int it = rank; it < 192; it += nwg) {
;         mod_item256(F, A, 48 * chunk + (it >> 2), 1024 * (it & 3), 32, (float*)(A.ws + WS_PART) + (size_t)(it & 3) * ((size_t)(DBATCH + 1) * 12288), 12288, 256 * (it >> 2), nullptr);
;         mod_group_finish(F, A, chunk, it >> 2);
;     }
; }
; __global__ void __launch_bounds__(NWAVES * 64, 2) mk_fwd(Args args) {
;     ...
;         for (int rep = 0; rep < REPS(1); ++rep) { if (rep) xcd_barrier(bar); mod_chunk_partials(F, args, 0, F.vcu, F.G); } } SEAM(1);
.Lp1_call:
	s_cmpk_lg_i32 s33, 0x100
	s_cbranch_scc1 .LBB0_97
	s_mov_b32 s98, 1
	v_writelane_b32 v253, s4, 0
	v_writelane_b32 v253, s5, 1
	v_writelane_b32 v253, s9, 2
	v_writelane_b32 v253, s18, 3
	s_movk_i32 s99, 0x2b00
	s_branch .Lconv_entry
